# mix phase: workgroups with bit 3 of the block index set walk their units in reverse order (memory-bound conv/SGU units overlap the other half's attention)
# speedup vs baseline: 1.0122x; 1.0015x over previous
; #define LAS __attribute__((address_space(3)))
; template <int L> __device__ __forceinline__ void phase_mix(const Args& args, LAS unsigned char* lds) {
;     const int tid = threadIdx.x, lane = tid & 63, wave = __builtin_amdgcn_readfirstlane(tid >> 6);
;     const int G = gridDim.x, blk = blockIdx.x;
;     unsigned char* ws = args.ws;
;     const bf16_t* segb = (const bf16_t*)(ws + WS_SEG);
;     bf16_t* OA = (bf16_t*)(ws + WS_O);
;     constexpr size_t SE = (size_t)MT * DH;
;     LAS float* btab = (LAS float*)(lds + 8 * ATT_WAVE_LDS + wave * 1536);
;     LAS unsigned char* wl = lds + (wave >> 1) * (2 * ATT_WAVE_LDS);
;     int cur_h = -1;
;     for (int u = blk; u < 1024 + 512 + 256; u += G) {
.LBB0_214:
	s_cmp_lt_i32 s22, 3
	s_cselect_b64 s[2:3], -1, 0
	s_cmp_gt_i32 s23, 2
	s_cselect_b64 s[4:5], -1, 0
	s_and_b64 s[2:3], s[2:3], s[4:5]
	s_andn2_b64 vcc, exec, s[2:3]
	s_cbranch_vccnz .LBB0_313
	s_load_dword s74, s[0:1], 0x88
	s_waitcnt lgkmcnt(0)
	s_add_u32 s10, s0, 0x88
	s_addc_u32 s11, s1, 0
	s_cmpk_gt_i32 s85, 0x6ff
	v_readfirstlane_b32 s6, v217
	s_cbranch_scc1 .LBB0_263
	s_lshr_b32 s2, s6, 6
	s_add_u32 s24, s20, 0xf200000
	s_addc_u32 s25, s21, 0
	s_add_u32 s26, s20, 0x31200000
	s_addc_u32 s27, s21, 0
	s_mulk_i32 s2, 0x600
	s_lshr_b32 s76, s6, 7
	s_add_i32 s7, s2, 0
	s_mul_i32 s2, s76, 0x9000
	s_add_i32 s75, s7, 0x24000
	s_add_i32 s77, s2, 0
	s_add_u32 s30, s20, 0x1f200000
	s_addc_u32 s31, s21, 0
	s_add_u32 s34, s20, 0x23200000
	s_addc_u32 s35, s21, 0
	s_add_u32 s36, s20, 0x35200000
	s_addc_u32 s37, s21, 0
	s_add_u32 s38, s20, 0x17200000
	s_addc_u32 s39, s21, 0
	s_add_u32 s40, s20, 0x19200000
	s_addc_u32 s41, s21, 0
	s_add_u32 s42, s20, 0x1b200000
	s_addc_u32 s43, s21, 0
	s_add_u32 s44, s20, 0x1d200000
	s_addc_u32 s45, s21, 0
	s_add_u32 s46, s20, 0x33200000
	s_addc_u32 s47, s21, 0
	s_bfe_u32 s8, s6, 0x10006
	s_add_u32 s48, s20, 0x15200000
	s_addc_u32 s49, s21, 0
	s_lshl_b32 s78, s8, 5
	v_and_b32_e32 v3, 3, v217
	s_bitcmp1_b32 s6, 6
	v_lshlrev_b32_e32 v4, 3, v3
	v_lshlrev_b32_e32 v157, 4, v3
	v_lshrrev_b32_e32 v3, 4, v217
	v_mov_b32_e32 v5, 0xffff8000
	v_lshlrev_b32_e32 v6, 1, v217
	v_lshrrev_b32_e32 v7, 1, v217
	s_cselect_b64 s[50:51], -1, 0
	s_add_u32 s52, s20, 0x37400000
	v_bfe_u32 v1, v217, 5, 1
	v_and_or_b32 v161, v3, 56, v5
	v_and_b32_e32 v5, 19, v217
	v_and_b32_e32 v6, 8, v6
	v_and_b32_e32 v8, 4, v7
	s_addc_u32 s53, s21, 0
	s_load_dwordx8 s[12:19], s[0:1], 0x18
	v_and_b32_e32 v131, 31, v217
	v_lshlrev_b32_e32 v154, 3, v217
	v_lshlrev_b32_e32 v130, 3, v1
	v_lshl_add_u32 v158, v1, 6, 0
	v_or3_b32 v5, v6, v5, v8
	s_add_u32 s54, s20, 0x11200000
	s_movk_i32 s6, 0x90
	v_lshlrev_b32_e32 v167, 4, v1
	v_mov_b32_e32 v1, s77
	s_mulk_i32 s8, 0x4800
	v_and_b32_e32 v160, 0x3f8, v154
	s_addc_u32 s55, s21, 0
	v_mul_u32_u24_e32 v166, 0x90, v5
	v_mad_u32_u24 v5, v5, s6, v1
	v_mad_u32_u24 v1, v131, s6, v1
	s_add_i32 s6, s77, s8
	s_load_dwordx2 s[8:9], s[0:1], 0x40
	v_mov_b32_e32 v133, 0
	v_lshlrev_b32_e32 v132, 1, v160
	v_and_b32_e32 v3, 7, v217
	v_lshl_add_u64 v[134:135], s[40:41], 0, v[132:133]
	v_lshl_add_u64 v[136:137], s[42:43], 0, v[132:133]
	v_lshlrev_b32_e32 v138, 3, v3
	v_lshlrev_b32_e32 v3, 4, v3
	v_lshlrev_b32_e32 v132, 2, v160
	s_lshl_b32 s79, s85, 6
	s_lshl_b32 s80, s74, 6
	s_lshl_b32 s81, s85, 2
	s_lshl_b32 s82, s74, 2
	v_add_u32_e32 v6, s6, v130
	v_add_u32_e32 v168, s6, v3
	s_waitcnt lgkmcnt(0)
	v_lshl_add_u64 v[140:141], s[14:15], 0, v[132:133]
	s_mov_b64 s[14:15], 0x1000
	s_add_u32 s6, s20, 0x39600060
	v_lshl_add_u64 v[142:143], v[140:141], 0, s[14:15]
	s_mov_b64 s[14:15], 0x2000
	v_writelane_b32 v244, s6, 2
	s_addc_u32 s6, s21, 0
	v_lshl_add_u64 v[144:145], v[140:141], 0, s[14:15]
	s_add_u32 s14, s8, 0x80
	s_addc_u32 s15, s9, 0
	v_bfe_u32 v162, v217, 3, 3
	v_or_b32_e32 v173, s78, v131
	v_and_b32_e32 v9, 15, v217
	v_writelane_b32 v244, s6, 4
	s_add_u32 s6, s20, 0x39600080
	v_and_b32_e32 v0, 63, v217
	v_bfe_u32 v2, v217, 2, 4
	v_mul_u32_u24_e32 v163, 0x90, v162
	v_or_b32_e32 v169, 8, v162
	v_sub_u32_e32 v8, v173, v130
	v_lshlrev_b32_e32 v132, 4, v9
	v_writelane_b32 v244, s6, 5
	s_addc_u32 s6, s21, 0
	v_cmp_gt_u32_e64 s[2:3], 16, v0
	s_movk_i32 s4, 0x80
	v_mul_u32_u24_e32 v159, 0x50, v2
	v_add3_u32 v164, s77, v3, v163
	v_mul_u32_u24_e32 v165, 0x90, v131
	v_mul_u32_u24_e32 v3, 0x90, v169
	v_lshl_add_u32 v172, v0, 2, s75
	v_lshl_add_u64 v[146:147], s[20:21], 0, v[132:133]
	v_lshlrev_b32_e32 v132, 8, v131
	v_lshl_or_b32 v175, v2, 10, v4
	s_add_u32 s56, s8, 0x180
	v_lshl_add_u32 v2, v8, 2, s7
	v_lshlrev_b32_e32 v178, 2, v0
	v_mbcnt_lo_u32_b32 v0, -1, 0
	s_mov_b32 s29, 0
	v_bfe_u32 v139, v217, 4, 2
	v_and_b32_e32 v155, 0x78, v154
	v_cmp_gt_u32_e64 s[4:5], s4, v217
	v_mul_u32_u24_e32 v156, 0x50, v131
	v_or_b32_e32 v170, 16, v162
	v_or_b32_e32 v171, 24, v162
	v_or_b32_e32 v174, 0x1c00, v154
	v_and_b32_e32 v148, 16, v7
	v_mov_b32_e32 v149, v133
	v_lshl_add_u64 v[150:151], s[20:21], 0, v[132:133]
	s_addc_u32 s57, s9, 0
	v_add_u32_e32 v176, 0x24720, v2
	s_mov_b32 s83, -1
	s_mov_b32 s86, 0x8080
	s_mov_b32 s87, 0x39640000
	s_mov_b32 s88, 0x39660000
	s_mov_b32 s89, 0x39680000
	s_mov_b32 s90, 0x396a0000
	s_mov_b32 s91, 0x396c0000
	s_mov_b32 s92, 0x396e0000
	v_mov_b32_e32 v177, 0x260
	s_mov_b32 s95, 0x37204000
	s_mov_b32 s96, 0x37202000
	s_mov_b64 s[58:59], 0x8000
	s_mov_b64 s[60:61], 0x404000
	s_mov_b64 s[62:63], 0x200
	s_mov_b32 s97, 0x37206000
	s_mov_b32 s93, 0x37200000
	v_add_u32_e32 v179, v1, v167
	s_mov_b32 s94, 0x41000000
	v_add_u32_e32 v180, v6, v165
	v_add_u32_e32 v181, v168, v3
	v_mbcnt_hi_u32_b32 v182, -1, v0
	v_add_u32_e32 v183, v5, v167
	s_mov_b32 s84, s85
	s_cmpk_lg_u32 s74, 0x100
	s_cbranch_scc1 .Lmix0_fwd
	s_bitcmp1_b32 s85, 3
	s_cbranch_scc0 .Lmix0_fwd
	s_addk_i32 s84, 0x600
	s_lshl_b32 s79, s84, 6
	s_lshl_b32 s81, s84, 2
	s_sub_i32 s74, 0, s74
	s_sub_i32 s80, 0, s80
	s_sub_i32 s82, 0, s82
.Lmix0_fwd:
	s_branch .LBB0_219
; #define LAS __attribute__((address_space(3)))
; __device__ __forceinline__ unsigned pk2(float lo, float hi) { f32x2 v = {lo, hi}; bf16x2_t b = __builtin_convertvector(v, bf16x2_t); return __builtin_bit_cast(unsigned, b); }
; __device__ __forceinline__ float bflo(unsigned u) { return __uint_as_float(u << 16); }
; __device__ __forceinline__ float bfhi(unsigned u) { return __uint_as_float(u & 0xffff0000u); }
; __device__ __forceinline__ void attn_item(const bf16_t* __restrict__ Q, const bf16_t* __restrict__ Kb, const bf16_t* __restrict__ VT, const bf16_t* __restrict__ GA, ...
;     ...
;     const float l = lrun + __shfl_xor(lrun, 32);
;     const float inv = 1.0f / l;
;     LAS unsigned char* Ot = pl + half * ATT_WAVE_LDS;
; #pragma unroll
;     for (int g = 0; g < 4; ++g) {
; #pragma unroll
;         for (int db = 0; db < 2; ++db) {
;             const f32x16& o = db ? o1 : o0;
;             u32x2 w; w.x = pk2(o[4 * g + 0] * inv, o[4 * g + 1] * inv); w.y = pk2(o[4 * g + 2] * inv, o[4 * g + 3] * inv);
;             *(LAS u32x2*)(Ot + r * ATP + (db * 32 + 8 * g + 4 * hh) * 2) = w;
;         }
;     }
; #pragma unroll
;     for (int i = 0; i < 4; ++i) {
;         const int row = rl + 8 * i;
;         const size_t a = (size_t)(tokq + row) * DH + h * 64 + cl * 8;
;         const u32x4 gg = *(const u32x4*)(GA + a);
;         const u32x4 ov = *(const LAS u32x4*)(Ot + row * ATP + cl * 16);
;         u32x4 w; w.x = pk2(bflo(ov.x) * bflo(gg.x), bfhi(ov.x) * bfhi(gg.x)); w.y = pk2(bflo(ov.y) * bflo(gg.y), bfhi(ov.y) * bfhi(gg.y));
;         w.z = pk2(bflo(ov.z) * bflo(gg.z), bfhi(ov.z) * bfhi(gg.z)); w.w = pk2(bflo(ov.w) * bflo(gg.w), bfhi(ov.w) * bfhi(gg.w));
;         *(u32x4*)(OA + a) = w;
;     }
.LBB0_217:
	v_or_b32_e32 v0, s65, v162
	v_ashrrev_i32_e32 v1, 31, v0
	v_mov_b32_e32 v47, s9
	v_or_b32_e32 v46, s8, v138
	v_lshlrev_b64 v[0:1], 10, v[0:1]
	v_lshl_add_u64 v[0:1], v[46:47], 0, v[0:1]
	v_lshlrev_b64 v[0:1], 1, v[0:1]
	v_lshl_add_u64 v[34:35], s[48:49], 0, v[0:1]
	global_load_dwordx4 v[34:37], v[34:35], off
	v_cmp_lt_i32_e32 vcc, v184, v185
	v_or_b32_e32 v38, s65, v169
	v_or_b32_e32 v40, s65, v170
	v_cndmask_b32_e32 v39, v182, v184, vcc
	v_lshlrev_b32_e32 v42, 2, v39
	ds_bpermute_b32 v44, v42, v187
	v_ashrrev_i32_e32 v39, 31, v38
	v_lshlrev_b64 v[38:39], 10, v[38:39]
	v_ashrrev_i32_e32 v41, 31, v40
	v_lshl_add_u64 v[38:39], v[46:47], 0, v[38:39]
	s_waitcnt lgkmcnt(0)
	v_add_f32_e32 v52, v187, v44
	v_lshlrev_b64 v[40:41], 10, v[40:41]
	v_lshlrev_b64 v[48:49], 1, v[38:39]
	v_div_scale_f32 v54, s[8:9], v52, v52, 1.0
	v_lshl_add_u64 v[40:41], v[46:47], 0, v[40:41]
	v_lshl_add_u64 v[38:39], s[48:49], 0, v[48:49]
	v_rcp_f32_e32 v55, v54
	v_lshlrev_b64 v[50:51], 1, v[40:41]
	global_load_dwordx4 v[38:41], v[38:39], off
	v_div_scale_f32 v56, vcc, 1.0, v52, 1.0
	v_fma_f32 v57, -v54, v55, 1.0
	v_fmac_f32_e32 v55, v57, v55
	v_mul_f32_e32 v57, v56, v55
	v_fma_f32 v58, -v54, v57, v56
	v_fmac_f32_e32 v57, v58, v55
	v_lshl_add_u64 v[42:43], s[48:49], 0, v[50:51]
	v_fma_f32 v54, -v54, v57, v56
	global_load_dwordx4 v[42:45], v[42:43], off
	v_div_fmas_f32 v54, v54, v55, v57
	v_add_u32_e32 v53, v168, v163
	v_div_fixup_f32 v52, v54, v52, 1.0
	v_pk_mul_f32 v[2:3], v[2:3], v[52:53] op_sel_hi:[1,0]
	v_pk_mul_f32 v[4:5], v[4:5], v[52:53] op_sel_hi:[1,0]
	v_pk_mul_f32 v[6:7], v[6:7], v[52:53] op_sel_hi:[1,0]
	v_pk_mul_f32 v[8:9], v[8:9], v[52:53] op_sel_hi:[1,0]
	v_pk_mul_f32 v[18:19], v[18:19], v[52:53] op_sel_hi:[1,0]
	v_pk_mul_f32 v[20:21], v[20:21], v[52:53] op_sel_hi:[1,0]
	v_pk_mul_f32 v[22:23], v[22:23], v[52:53] op_sel_hi:[1,0]
	v_pk_mul_f32 v[24:25], v[24:25], v[52:53] op_sel_hi:[1,0]
	v_pk_mul_f32 v[10:11], v[10:11], v[52:53] op_sel_hi:[1,0]
	v_pk_mul_f32 v[12:13], v[12:13], v[52:53] op_sel_hi:[1,0]
	v_pk_mul_f32 v[26:27], v[26:27], v[52:53] op_sel_hi:[1,0]
	v_pk_mul_f32 v[28:29], v[28:29], v[52:53] op_sel_hi:[1,0]
	v_pk_mul_f32 v[14:15], v[14:15], v[52:53] op_sel_hi:[1,0]
	v_pk_mul_f32 v[16:17], v[16:17], v[52:53] op_sel_hi:[1,0]
	v_pk_mul_f32 v[30:31], v[30:31], v[52:53] op_sel_hi:[1,0]
	v_pk_mul_f32 v[32:33], v[32:33], v[52:53] op_sel_hi:[1,0]
	v_cvt_pk_bf16_f32 v2, v2, v3
	v_cvt_pk_bf16_f32 v3, v4, v5
	v_cvt_pk_bf16_f32 v6, v6, v7
	v_cvt_pk_bf16_f32 v7, v8, v9
	v_cvt_pk_bf16_f32 v4, v18, v19
	v_cvt_pk_bf16_f32 v5, v20, v21
	v_cvt_pk_bf16_f32 v8, v22, v23
	v_cvt_pk_bf16_f32 v9, v24, v25
	v_cvt_pk_bf16_f32 v10, v10, v11
	v_cvt_pk_bf16_f32 v11, v12, v13
	v_cvt_pk_bf16_f32 v12, v26, v27
	v_cvt_pk_bf16_f32 v13, v28, v29
	v_cvt_pk_bf16_f32 v14, v14, v15
	v_cvt_pk_bf16_f32 v15, v16, v17
	v_cvt_pk_bf16_f32 v16, v30, v31
	v_cvt_pk_bf16_f32 v17, v32, v33
	ds_write2_b64 v180, v[2:3], v[6:7] offset1:2
	ds_write2_b64 v180, v[4:5], v[8:9] offset0:8 offset1:10
	ds_write2_b64 v180, v[10:11], v[14:15] offset0:4 offset1:6
	ds_write2_b64 v180, v[12:13], v[16:17] offset0:12 offset1:14
	v_or_b32_e32 v6, s65, v171
	v_ashrrev_i32_e32 v7, 31, v6
	v_lshlrev_b64 v[6:7], 10, v[6:7]
	v_lshl_add_u64 v[6:7], v[46:47], 0, v[6:7]
	v_lshlrev_b64 v[14:15], 1, v[6:7]
	v_lshl_add_u64 v[6:7], s[48:49], 0, v[14:15]
	global_load_dwordx4 v[6:9], v[6:7], off
	ds_read_b128 v[2:5], v53
	v_lshl_add_u64 v[0:1], s[26:27], 0, v[0:1]
	s_waitcnt lgkmcnt(0)
	v_lshlrev_b32_e32 v10, 16, v2
	v_and_b32_e32 v11, 0xffff0000, v2
	s_waitcnt vmcnt(3)
; #define LAS __attribute__((address_space(3)))
; __device__ __forceinline__ unsigned pk2(float lo, float hi) { f32x2 v = {lo, hi}; bf16x2_t b = __builtin_convertvector(v, bf16x2_t); return __builtin_bit_cast(unsigned, b); }
; __device__ __forceinline__ float bflo(unsigned u) { return __uint_as_float(u << 16); }
; __device__ __forceinline__ float bfhi(unsigned u) { return __uint_as_float(u & 0xffff0000u); }
; #define ATT_BAR() asm volatile("s_waitcnt lgkmcnt(0)\n\ts_barrier" ::: "memory")
; __device__ __forceinline__ void attn_item(const bf16_t* __restrict__ Q, const bf16_t* __restrict__ Kb, const bf16_t* __restrict__ VT, const bf16_t* __restrict__ GA, ...
;     ...
;     for (int i = 0; i < 4; ++i) {
;         const int row = rl + 8 * i;
;         const size_t a = (size_t)(tokq + row) * DH + h * 64 + cl * 8;
;         const u32x4 gg = *(const u32x4*)(GA + a);
;         const u32x4 ov = *(const LAS u32x4*)(Ot + row * ATP + cl * 16);
;         u32x4 w; w.x = pk2(bflo(ov.x) * bflo(gg.x), bfhi(ov.x) * bfhi(gg.x)); w.y = pk2(bflo(ov.y) * bflo(gg.y), bfhi(ov.y) * bfhi(gg.y));
;         w.z = pk2(bflo(ov.z) * bflo(gg.z), bfhi(ov.z) * bfhi(gg.z)); w.w = pk2(bflo(ov.w) * bflo(gg.w), bfhi(ov.w) * bfhi(gg.w));
;         *(u32x4*)(OA + a) = w;
;     }
;     ATT_BAR();
; template <int L> __device__ __forceinline__ void phase_mix(const Args& args, LAS unsigned char* lds) {
;     ...
;     for (int u = blk; u < 1024 + 512 + 256; u += G) {
	v_lshlrev_b32_e32 v12, 16, v34
	v_and_b32_e32 v13, 0xffff0000, v34
	v_pk_mul_f32 v[10:11], v[12:13], v[10:11]
	v_lshlrev_b32_e32 v12, 16, v35
	v_cvt_pk_bf16_f32 v2, v10, v11
	v_lshlrev_b32_e32 v10, 16, v3
	v_and_b32_e32 v11, 0xffff0000, v3
	v_and_b32_e32 v13, 0xffff0000, v35
	v_pk_mul_f32 v[10:11], v[12:13], v[10:11]
	v_lshlrev_b32_e32 v12, 16, v36
	v_cvt_pk_bf16_f32 v3, v10, v11
	v_lshlrev_b32_e32 v10, 16, v4
	v_and_b32_e32 v11, 0xffff0000, v4
	v_and_b32_e32 v13, 0xffff0000, v36
	v_pk_mul_f32 v[10:11], v[12:13], v[10:11]
	v_lshlrev_b32_e32 v12, 16, v37
	v_cvt_pk_bf16_f32 v4, v10, v11
	v_lshlrev_b32_e32 v10, 16, v5
	v_and_b32_e32 v11, 0xffff0000, v5
	v_and_b32_e32 v13, 0xffff0000, v37
	v_pk_mul_f32 v[16:17], v[12:13], v[10:11]
	ds_read_b128 v[10:13], v181
	v_cvt_pk_bf16_f32 v5, v16, v17
	global_store_dwordx4 v[0:1], v[2:5], off
	ds_read_b128 v[0:3], v181 offset:1152
	s_waitcnt vmcnt(3)
	v_lshlrev_b32_e32 v16, 16, v38
	s_waitcnt lgkmcnt(1)
	v_lshlrev_b32_e32 v4, 16, v10
	v_and_b32_e32 v5, 0xffff0000, v10
	v_and_b32_e32 v17, 0xffff0000, v38
	v_pk_mul_f32 v[4:5], v[16:17], v[4:5]
	v_lshlrev_b32_e32 v16, 16, v39
	v_cvt_pk_bf16_f32 v10, v4, v5
	v_lshlrev_b32_e32 v4, 16, v11
	v_and_b32_e32 v5, 0xffff0000, v11
	v_and_b32_e32 v17, 0xffff0000, v39
	v_pk_mul_f32 v[4:5], v[16:17], v[4:5]
	v_lshlrev_b32_e32 v16, 16, v40
	v_cvt_pk_bf16_f32 v11, v4, v5
	v_lshlrev_b32_e32 v4, 16, v12
	v_and_b32_e32 v5, 0xffff0000, v12
	v_and_b32_e32 v17, 0xffff0000, v40
	v_pk_mul_f32 v[4:5], v[16:17], v[4:5]
	v_lshlrev_b32_e32 v16, 16, v41
	v_cvt_pk_bf16_f32 v12, v4, v5
	v_lshlrev_b32_e32 v4, 16, v13
	v_and_b32_e32 v5, 0xffff0000, v13
	v_and_b32_e32 v17, 0xffff0000, v41
	v_pk_mul_f32 v[4:5], v[16:17], v[4:5]
	s_waitcnt vmcnt(2)
	v_lshlrev_b32_e32 v16, 16, v45
	v_cvt_pk_bf16_f32 v13, v4, v5
	v_lshl_add_u64 v[4:5], s[26:27], 0, v[48:49]
	global_store_dwordx4 v[4:5], v[10:13], off
	s_waitcnt lgkmcnt(0)
	v_lshlrev_b32_e32 v4, 16, v0
	v_and_b32_e32 v5, 0xffff0000, v0
	v_lshlrev_b32_e32 v10, 16, v42
	v_and_b32_e32 v11, 0xffff0000, v42
	v_pk_mul_f32 v[4:5], v[10:11], v[4:5]
	v_lshlrev_b32_e32 v10, 16, v43
	v_cvt_pk_bf16_f32 v0, v4, v5
	v_lshlrev_b32_e32 v4, 16, v1
	v_and_b32_e32 v5, 0xffff0000, v1
	v_and_b32_e32 v11, 0xffff0000, v43
	v_pk_mul_f32 v[4:5], v[10:11], v[4:5]
	v_lshlrev_b32_e32 v10, 16, v44
	v_cvt_pk_bf16_f32 v1, v4, v5
	v_lshlrev_b32_e32 v4, 16, v2
	v_and_b32_e32 v5, 0xffff0000, v2
	v_and_b32_e32 v11, 0xffff0000, v44
	v_pk_mul_f32 v[4:5], v[10:11], v[4:5]
	ds_read_b128 v[10:13], v181 offset:2304
	v_cvt_pk_bf16_f32 v2, v4, v5
	v_lshlrev_b32_e32 v4, 16, v3
	v_and_b32_e32 v5, 0xffff0000, v3
	v_and_b32_e32 v17, 0xffff0000, v45
	v_pk_mul_f32 v[4:5], v[16:17], v[4:5]
	s_nop 0
	v_cvt_pk_bf16_f32 v3, v4, v5
	v_lshl_add_u64 v[4:5], s[26:27], 0, v[50:51]
	global_store_dwordx4 v[4:5], v[0:3], off
	s_waitcnt vmcnt(3)
	v_lshlrev_b32_e32 v4, 16, v7
	v_and_b32_e32 v5, 0xffff0000, v7
	s_waitcnt lgkmcnt(0)
	v_lshlrev_b32_e32 v0, 16, v10
	v_and_b32_e32 v1, 0xffff0000, v10
	v_lshlrev_b32_e32 v2, 16, v6
	v_and_b32_e32 v3, 0xffff0000, v6
	v_pk_mul_f32 v[0:1], v[2:3], v[0:1]
	v_lshlrev_b32_e32 v2, 16, v11
	v_and_b32_e32 v3, 0xffff0000, v11
	v_pk_mul_f32 v[2:3], v[4:5], v[2:3]
	v_cvt_pk_bf16_f32 v0, v0, v1
	v_cvt_pk_bf16_f32 v1, v2, v3
	v_lshlrev_b32_e32 v2, 16, v12
	v_and_b32_e32 v3, 0xffff0000, v12
	v_lshlrev_b32_e32 v4, 16, v8
	v_and_b32_e32 v5, 0xffff0000, v8
	v_pk_mul_f32 v[2:3], v[4:5], v[2:3]
	v_lshlrev_b32_e32 v4, 16, v13
	v_and_b32_e32 v5, 0xffff0000, v13
	v_lshlrev_b32_e32 v6, 16, v9
	v_and_b32_e32 v7, 0xffff0000, v9
	v_pk_mul_f32 v[4:5], v[6:7], v[4:5]
	v_cvt_pk_bf16_f32 v2, v2, v3
	v_cvt_pk_bf16_f32 v3, v4, v5
	v_lshl_add_u64 v[4:5], s[26:27], 0, v[14:15]
	global_store_dwordx4 v[4:5], v[0:3], off
	s_waitcnt lgkmcnt(0)
	s_barrier
.LBB0_218:
	s_add_i32 s84, s84, s74
	s_add_i32 s79, s79, s80
	s_add_i32 s81, s81, s82
	s_cmpk_lt_u32 s84, 0x700
	s_cbranch_scc0 .LBB0_263

; #define LAS __attribute__((address_space(3)))
; __device__ __forceinline__ void attn_item(const bf16_t* __restrict__ Q, const bf16_t* __restrict__ Kb, const bf16_t* __restrict__ VT, const bf16_t* __restrict__ GA, ...
;     const int r = lane & 31, hh = lane >> 5;
;     const int rl = lane >> 3, cl = lane & 7;
;     const int tokq = b * SEQ + c * 64 + half * 32;
;     const int qloc = half * 32 + r;
;     const int pr = (r & ~12) | ((r & 4) << 1) | ((r & 8) >> 1);
;     const int jmin = c >= 8 ? 0 : 8 - c;
;     const int tk0 = b * SEQ + (c - 8 + jmin) * 64;
;     const bf16_t* tg = half ? VT + (size_t)(h * 64 + rl) * PT + tk0 + cl * 8 : Kb + (size_t)(tk0 + rl) * DH + h * 64 + cl * 8;
;     const size_t rstep = half ? (size_t)8 * PT : (size_t)8 * DH;
;     const size_t tstep = half ? (size_t)64 : (size_t)64 * DH;
;     const int stoff = (half ? 64 * ATP : 0) + rl * ATP + cl * 16;
; template <int L> __device__ __forceinline__ void phase_mix(const Args& args, LAS unsigned char* lds) {
;     const int tid = threadIdx.x, lane = tid & 63, wave = __builtin_amdgcn_readfirstlane(tid >> 6);
;     const int G = gridDim.x, blk = blockIdx.x;
;     unsigned char* ws = args.ws;
;     const bf16_t* segb = (const bf16_t*)(ws + WS_SEG);
;     bf16_t* OA = (bf16_t*)(ws + WS_O);
;     constexpr size_t SE = (size_t)MT * DH;
;     LAS float* btab = (LAS float*)(lds + 8 * ATT_WAVE_LDS + wave * 1536);
;     LAS unsigned char* wl = lds + (wave >> 1) * (2 * ATT_WAVE_LDS);
;     int cur_h = -1;
;     for (int u = blk; u < 1024 + 512 + 256; u += G) {
.LBB0_638:
	s_cmp_lt_i32 s22, 8
	s_cselect_b64 s[2:3], -1, 0
	s_cmp_gt_i32 s23, 7
	s_cselect_b64 s[4:5], -1, 0
	s_and_b64 s[2:3], s[2:3], s[4:5]
	s_andn2_b64 vcc, exec, s[2:3]
	s_cbranch_vccnz .LBB0_737
	s_load_dword s74, s[0:1], 0x88
	s_waitcnt lgkmcnt(0)
	s_add_u32 s10, s0, 0x88
	s_addc_u32 s11, s1, 0
	s_cmpk_gt_i32 s85, 0x6ff
	v_readfirstlane_b32 s6, v217
	s_cbranch_scc1 .LBB0_687
	s_lshr_b32 s2, s6, 6
	s_add_u32 s24, s20, 0xf200000
	s_addc_u32 s25, s21, 0
	s_add_u32 s26, s20, 0x31200000
	s_addc_u32 s27, s21, 0
	s_mulk_i32 s2, 0x600
	s_lshr_b32 s76, s6, 7
	s_add_i32 s7, s2, 0
	s_mul_i32 s2, s76, 0x9000
	s_add_i32 s75, s7, 0x24000
	s_add_i32 s77, s2, 0
	s_add_u32 s30, s20, 0x1f200000
	s_addc_u32 s31, s21, 0
	s_add_u32 s34, s20, 0x23200000
	s_addc_u32 s35, s21, 0
	s_add_u32 s36, s20, 0x35200000
	s_addc_u32 s37, s21, 0
	s_add_u32 s38, s20, 0x17200000
	s_addc_u32 s39, s21, 0
	s_add_u32 s40, s20, 0x19200000
	s_addc_u32 s41, s21, 0
	s_add_u32 s42, s20, 0x1b200000
	s_addc_u32 s43, s21, 0
	s_add_u32 s44, s20, 0x1d200000
	s_addc_u32 s45, s21, 0
	s_add_u32 s46, s20, 0x33200000
	s_addc_u32 s47, s21, 0
	s_bfe_u32 s8, s6, 0x10006
	s_add_u32 s48, s20, 0x15200000
	s_addc_u32 s49, s21, 0
	s_lshl_b32 s78, s8, 5
	v_and_b32_e32 v2, 3, v217
	s_bitcmp1_b32 s6, 6
	s_load_dwordx8 s[12:19], s[0:1], 0x18
	v_lshlrev_b32_e32 v154, 3, v217
	v_lshlrev_b32_e32 v5, 3, v2
	v_lshlrev_b32_e32 v157, 4, v2
	v_lshrrev_b32_e32 v2, 4, v217
	v_mov_b32_e32 v3, 0xffff8000
	v_lshlrev_b32_e32 v6, 1, v217
	v_lshrrev_b32_e32 v7, 1, v217
	s_cselect_b64 s[50:51], -1, 0
	s_add_u32 s52, s20, 0x37400000
	v_bfe_u32 v1, v217, 5, 1
	v_and_b32_e32 v160, 0x3f8, v154
	v_and_or_b32 v161, v2, 56, v3
	v_and_b32_e32 v3, 19, v217
	v_and_b32_e32 v6, 8, v6
	v_and_b32_e32 v8, 4, v7
	s_addc_u32 s53, s21, 0
	v_and_b32_e32 v131, 31, v217
	v_lshlrev_b32_e32 v130, 3, v1
	v_mov_b32_e32 v133, 0
	v_lshl_add_u32 v158, v1, 6, 0
	v_lshlrev_b32_e32 v132, 1, v160
	v_bfe_u32 v162, v217, 3, 3
	v_and_b32_e32 v2, 7, v217
	v_or3_b32 v3, v6, v3, v8
	s_add_u32 s54, s20, 0x11200000
	s_movk_i32 s6, 0x90
	v_lshlrev_b32_e32 v167, 4, v1
	v_mov_b32_e32 v1, s77
	s_mulk_i32 s8, 0x4800
	v_lshl_add_u64 v[134:135], s[40:41], 0, v[132:133]
	v_lshl_add_u64 v[136:137], s[42:43], 0, v[132:133]
	v_lshlrev_b32_e32 v138, 3, v2
	s_addc_u32 s55, s21, 0
	v_mul_u32_u24_e32 v163, 0x90, v162
	v_lshlrev_b32_e32 v2, 4, v2
	v_mad_u32_u24 v6, v3, s6, v1
	v_mad_u32_u24 v1, v131, s6, v1
	s_add_i32 s6, s77, s8
	v_lshlrev_b32_e32 v132, 2, v160
	v_add3_u32 v164, s77, v2, v163
	v_mul_u32_u24_e32 v166, 0x90, v3
	v_add_u32_e32 v168, s6, v2
	s_waitcnt lgkmcnt(0)
	v_lshl_add_u64 v[2:3], s[14:15], 0, v[132:133]
	s_mov_b64 s[14:15], 0x3000
	s_lshl_b32 s79, s85, 6
	s_lshl_b32 s80, s74, 6
	s_lshl_b32 s81, s85, 2
	s_lshl_b32 s82, s74, 2
	v_add_u32_e32 v8, s6, v130
	v_lshl_add_u64 v[140:141], v[2:3], 0, s[14:15]
	s_mov_b64 s[14:15], 0x4000
	s_add_u32 s6, s20, 0x39600060
	s_load_dwordx2 s[8:9], s[0:1], 0x40
	v_lshl_add_u64 v[142:143], v[2:3], 0, s[14:15]
	s_mov_b64 s[14:15], 0x5000
	v_writelane_b32 v244, s6, 2
	s_addc_u32 s6, s21, 0
	v_lshl_add_u64 v[144:145], v[2:3], 0, s[14:15]
	s_add_u32 s14, s18, 0x1000
	s_addc_u32 s15, s19, 0
	s_add_u32 s16, s16, 0x1000
	s_addc_u32 s17, s17, 0
	s_waitcnt lgkmcnt(0)
	s_add_u32 s18, s8, 0x1100
	s_addc_u32 s19, s9, 0
	v_or_b32_e32 v173, s78, v131
	v_and_b32_e32 v2, 15, v217
	v_writelane_b32 v244, s6, 4
	s_add_u32 s6, s20, 0x39600080
	v_and_b32_e32 v0, 63, v217
	v_or_b32_e32 v169, 8, v162
	v_sub_u32_e32 v10, v173, v130
	v_lshlrev_b32_e32 v132, 4, v2
	s_addc_u32 s86, s21, 0
	v_cmp_gt_u32_e64 s[2:3], 16, v0
	s_movk_i32 s4, 0x80
	v_bfe_u32 v4, v217, 2, 4
	v_mul_u32_u24_e32 v165, 0x90, v131
	v_mul_u32_u24_e32 v9, 0x90, v169
	v_lshl_add_u32 v172, v0, 2, s75
	v_lshl_add_u64 v[146:147], s[20:21], 0, v[132:133]
	v_lshlrev_b32_e32 v132, 8, v131
	s_add_u32 s56, s8, 0x1180
	v_lshl_add_u32 v2, v10, 2, s7
	v_lshlrev_b32_e32 v178, 2, v0
	v_mbcnt_lo_u32_b32 v0, -1, 0
	s_mov_b32 s29, 0
	v_bfe_u32 v139, v217, 4, 2
	v_and_b32_e32 v155, 0x78, v154
	v_cmp_gt_u32_e64 s[4:5], s4, v217
	v_mul_u32_u24_e32 v156, 0x50, v131
	v_mul_u32_u24_e32 v159, 0x50, v4
	v_or_b32_e32 v170, 16, v162
	v_or_b32_e32 v171, 24, v162
	v_or_b32_e32 v174, 0x1c00, v154
	v_and_b32_e32 v148, 16, v7
	v_mov_b32_e32 v149, v133
	v_lshl_add_u64 v[150:151], s[20:21], 0, v[132:133]
	v_lshl_or_b32 v175, v4, 10, v5
	v_writelane_b32 v244, s6, 5
	s_addc_u32 s57, s9, 0
	v_add_u32_e32 v176, 0x24720, v2
	s_mov_b32 s83, -1
	s_mov_b32 s87, 0x8080
	s_mov_b32 s88, 0x39640000
	s_mov_b32 s89, 0x39660000
	s_mov_b32 s90, 0x39680000
	s_mov_b32 s91, 0x396a0000
	s_mov_b32 s92, 0x396c0000
	s_mov_b32 s93, 0x396e0000
	v_mov_b32_e32 v177, 0x260
	s_mov_b32 s96, 0x37244000
	s_mov_b32 s97, 0x37242000
	s_mov_b64 s[58:59], 0x8000
	s_mov_b64 s[60:61], 0x404000
	s_mov_b64 s[62:63], 0x200
	s_mov_b32 s94, 0x37246000
	s_mov_b32 s95, 0x37240000
	v_add_u32_e32 v179, v1, v167
	s_mov_b32 s33, 0x41000000
	v_add_u32_e32 v180, v8, v165
	v_add_u32_e32 v181, v168, v9
	v_mbcnt_hi_u32_b32 v182, -1, v0
	v_add_u32_e32 v183, v6, v167
	s_mov_b32 s6, s85
	s_cmpk_lg_u32 s74, 0x100
	s_cbranch_scc1 .Lmix1_fwd
	s_bitcmp1_b32 s85, 3
	s_cbranch_scc0 .Lmix1_fwd
	s_addk_i32 s6, 0x600
	s_lshl_b32 s79, s6, 6
	s_lshl_b32 s81, s6, 2
	s_sub_i32 s74, 0, s74
	s_sub_i32 s80, 0, s80
	s_sub_i32 s82, 0, s82
.Lmix1_fwd:
	s_branch .LBB0_643
; #define LAS __attribute__((address_space(3)))
; __device__ __forceinline__ unsigned pk2(float lo, float hi) { f32x2 v = {lo, hi}; bf16x2_t b = __builtin_convertvector(v, bf16x2_t); return __builtin_bit_cast(unsigned, b); }
; __device__ __forceinline__ float bflo(unsigned u) { return __uint_as_float(u << 16); }
; __device__ __forceinline__ float bfhi(unsigned u) { return __uint_as_float(u & 0xffff0000u); }
; __device__ __forceinline__ void attn_item(const bf16_t* __restrict__ Q, const bf16_t* __restrict__ Kb, const bf16_t* __restrict__ VT, const bf16_t* __restrict__ GA, ...
;     ...
;     const float l = lrun + __shfl_xor(lrun, 32);
;     const float inv = 1.0f / l;
;     LAS unsigned char* Ot = pl + half * ATT_WAVE_LDS;
; #pragma unroll
;     for (int g = 0; g < 4; ++g) {
; #pragma unroll
;         for (int db = 0; db < 2; ++db) {
;             const f32x16& o = db ? o1 : o0;
;             u32x2 w; w.x = pk2(o[4 * g + 0] * inv, o[4 * g + 1] * inv); w.y = pk2(o[4 * g + 2] * inv, o[4 * g + 3] * inv);
;             *(LAS u32x2*)(Ot + r * ATP + (db * 32 + 8 * g + 4 * hh) * 2) = w;
;         }
;     }
; #pragma unroll
;     for (int i = 0; i < 4; ++i) {
;         const int row = rl + 8 * i;
;         const size_t a = (size_t)(tokq + row) * DH + h * 64 + cl * 8;
;         const u32x4 gg = *(const u32x4*)(GA + a);
;         const u32x4 ov = *(const LAS u32x4*)(Ot + row * ATP + cl * 16);
;         u32x4 w; w.x = pk2(bflo(ov.x) * bflo(gg.x), bfhi(ov.x) * bfhi(gg.x)); w.y = pk2(bflo(ov.y) * bflo(gg.y), bfhi(ov.y) * bfhi(gg.y));
.LBB0_641:
	v_or_b32_e32 v0, s65, v162
	v_ashrrev_i32_e32 v1, 31, v0
	v_mov_b32_e32 v47, s9
	v_or_b32_e32 v46, s8, v138
	v_lshlrev_b64 v[0:1], 10, v[0:1]
	v_lshl_add_u64 v[0:1], v[46:47], 0, v[0:1]
	v_lshlrev_b64 v[0:1], 1, v[0:1]
	v_lshl_add_u64 v[34:35], s[48:49], 0, v[0:1]
	global_load_dwordx4 v[34:37], v[34:35], off
	v_cmp_lt_i32_e32 vcc, v184, v185
	v_or_b32_e32 v38, s65, v169
	v_or_b32_e32 v40, s65, v170
	v_cndmask_b32_e32 v39, v182, v184, vcc
	v_lshlrev_b32_e32 v42, 2, v39
	ds_bpermute_b32 v44, v42, v187
	v_ashrrev_i32_e32 v39, 31, v38
	v_lshlrev_b64 v[38:39], 10, v[38:39]
	v_ashrrev_i32_e32 v41, 31, v40
	v_lshl_add_u64 v[38:39], v[46:47], 0, v[38:39]
	s_waitcnt lgkmcnt(0)
	v_add_f32_e32 v52, v187, v44
	v_lshlrev_b64 v[40:41], 10, v[40:41]
	v_lshlrev_b64 v[48:49], 1, v[38:39]
	v_div_scale_f32 v54, s[8:9], v52, v52, 1.0
	v_lshl_add_u64 v[40:41], v[46:47], 0, v[40:41]
	v_lshl_add_u64 v[38:39], s[48:49], 0, v[48:49]
	v_rcp_f32_e32 v55, v54
	v_lshlrev_b64 v[50:51], 1, v[40:41]
	global_load_dwordx4 v[38:41], v[38:39], off
	v_div_scale_f32 v56, vcc, 1.0, v52, 1.0
	v_fma_f32 v57, -v54, v55, 1.0
	v_fmac_f32_e32 v55, v57, v55
	v_mul_f32_e32 v57, v56, v55
	v_fma_f32 v58, -v54, v57, v56
	v_fmac_f32_e32 v57, v58, v55
	v_lshl_add_u64 v[42:43], s[48:49], 0, v[50:51]
	v_fma_f32 v54, -v54, v57, v56
	global_load_dwordx4 v[42:45], v[42:43], off
	v_div_fmas_f32 v54, v54, v55, v57
	v_add_u32_e32 v53, v168, v163
	v_div_fixup_f32 v52, v54, v52, 1.0
	v_pk_mul_f32 v[2:3], v[2:3], v[52:53] op_sel_hi:[1,0]
	v_pk_mul_f32 v[4:5], v[4:5], v[52:53] op_sel_hi:[1,0]
	v_pk_mul_f32 v[6:7], v[6:7], v[52:53] op_sel_hi:[1,0]
	v_pk_mul_f32 v[8:9], v[8:9], v[52:53] op_sel_hi:[1,0]
	v_pk_mul_f32 v[18:19], v[18:19], v[52:53] op_sel_hi:[1,0]
	v_pk_mul_f32 v[20:21], v[20:21], v[52:53] op_sel_hi:[1,0]
	v_pk_mul_f32 v[22:23], v[22:23], v[52:53] op_sel_hi:[1,0]
	v_pk_mul_f32 v[24:25], v[24:25], v[52:53] op_sel_hi:[1,0]
	v_pk_mul_f32 v[10:11], v[10:11], v[52:53] op_sel_hi:[1,0]
	v_pk_mul_f32 v[12:13], v[12:13], v[52:53] op_sel_hi:[1,0]
	v_pk_mul_f32 v[26:27], v[26:27], v[52:53] op_sel_hi:[1,0]
	v_pk_mul_f32 v[28:29], v[28:29], v[52:53] op_sel_hi:[1,0]
	v_pk_mul_f32 v[14:15], v[14:15], v[52:53] op_sel_hi:[1,0]
	v_pk_mul_f32 v[16:17], v[16:17], v[52:53] op_sel_hi:[1,0]
	v_pk_mul_f32 v[30:31], v[30:31], v[52:53] op_sel_hi:[1,0]
	v_pk_mul_f32 v[32:33], v[32:33], v[52:53] op_sel_hi:[1,0]
	v_cvt_pk_bf16_f32 v2, v2, v3
	v_cvt_pk_bf16_f32 v3, v4, v5
	v_cvt_pk_bf16_f32 v6, v6, v7
	v_cvt_pk_bf16_f32 v7, v8, v9
	v_cvt_pk_bf16_f32 v4, v18, v19
	v_cvt_pk_bf16_f32 v5, v20, v21
	v_cvt_pk_bf16_f32 v8, v22, v23
	v_cvt_pk_bf16_f32 v9, v24, v25
	v_cvt_pk_bf16_f32 v10, v10, v11
	v_cvt_pk_bf16_f32 v11, v12, v13
	v_cvt_pk_bf16_f32 v12, v26, v27
	v_cvt_pk_bf16_f32 v13, v28, v29
	v_cvt_pk_bf16_f32 v14, v14, v15
	v_cvt_pk_bf16_f32 v15, v16, v17
	v_cvt_pk_bf16_f32 v16, v30, v31
	v_cvt_pk_bf16_f32 v17, v32, v33
	ds_write2_b64 v180, v[2:3], v[6:7] offset1:2
	ds_write2_b64 v180, v[4:5], v[8:9] offset0:8 offset1:10
	ds_write2_b64 v180, v[10:11], v[14:15] offset0:4 offset1:6
	ds_write2_b64 v180, v[12:13], v[16:17] offset0:12 offset1:14
	v_or_b32_e32 v6, s65, v171
	v_ashrrev_i32_e32 v7, 31, v6
	v_lshlrev_b64 v[6:7], 10, v[6:7]
	v_lshl_add_u64 v[6:7], v[46:47], 0, v[6:7]
	v_lshlrev_b64 v[14:15], 1, v[6:7]
	v_lshl_add_u64 v[6:7], s[48:49], 0, v[14:15]
	global_load_dwordx4 v[6:9], v[6:7], off
	ds_read_b128 v[2:5], v53
	v_lshl_add_u64 v[0:1], s[26:27], 0, v[0:1]
	s_waitcnt lgkmcnt(0)
	v_lshlrev_b32_e32 v10, 16, v2
	v_and_b32_e32 v11, 0xffff0000, v2
	s_waitcnt vmcnt(3)
; #define LAS __attribute__((address_space(3)))
; __device__ __forceinline__ unsigned pk2(float lo, float hi) { f32x2 v = {lo, hi}; bf16x2_t b = __builtin_convertvector(v, bf16x2_t); return __builtin_bit_cast(unsigned, b); }
; __device__ __forceinline__ float bflo(unsigned u) { return __uint_as_float(u << 16); }
; __device__ __forceinline__ float bfhi(unsigned u) { return __uint_as_float(u & 0xffff0000u); }
; #define ATT_BAR() asm volatile("s_waitcnt lgkmcnt(0)\n\ts_barrier" ::: "memory")
; __device__ __forceinline__ void attn_item(const bf16_t* __restrict__ Q, const bf16_t* __restrict__ Kb, const bf16_t* __restrict__ VT, const bf16_t* __restrict__ GA, ...
;     ...
; #pragma unroll
;     for (int i = 0; i < 4; ++i) {
;         const int row = rl + 8 * i;
;         const size_t a = (size_t)(tokq + row) * DH + h * 64 + cl * 8;
;         const u32x4 gg = *(const u32x4*)(GA + a);
;         const u32x4 ov = *(const LAS u32x4*)(Ot + row * ATP + cl * 16);
;         u32x4 w; w.x = pk2(bflo(ov.x) * bflo(gg.x), bfhi(ov.x) * bfhi(gg.x)); w.y = pk2(bflo(ov.y) * bflo(gg.y), bfhi(ov.y) * bfhi(gg.y));
;         w.z = pk2(bflo(ov.z) * bflo(gg.z), bfhi(ov.z) * bfhi(gg.z)); w.w = pk2(bflo(ov.w) * bflo(gg.w), bfhi(ov.w) * bfhi(gg.w));
;         *(u32x4*)(OA + a) = w;
;     }
;     ATT_BAR();
; template <int L> __device__ __forceinline__ void phase_mix(const Args& args, LAS unsigned char* lds) {
;     ...
;     for (int u = blk; u < 1024 + 512 + 256; u += G) {
	v_lshlrev_b32_e32 v12, 16, v34
	v_and_b32_e32 v13, 0xffff0000, v34
	v_pk_mul_f32 v[10:11], v[12:13], v[10:11]
	v_lshlrev_b32_e32 v12, 16, v35
	v_cvt_pk_bf16_f32 v2, v10, v11
	v_lshlrev_b32_e32 v10, 16, v3
	v_and_b32_e32 v11, 0xffff0000, v3
	v_and_b32_e32 v13, 0xffff0000, v35
	v_pk_mul_f32 v[10:11], v[12:13], v[10:11]
	v_lshlrev_b32_e32 v12, 16, v36
	v_cvt_pk_bf16_f32 v3, v10, v11
	v_lshlrev_b32_e32 v10, 16, v4
	v_and_b32_e32 v11, 0xffff0000, v4
	v_and_b32_e32 v13, 0xffff0000, v36
	v_pk_mul_f32 v[10:11], v[12:13], v[10:11]
	v_lshlrev_b32_e32 v12, 16, v37
	v_cvt_pk_bf16_f32 v4, v10, v11
	v_lshlrev_b32_e32 v10, 16, v5
	v_and_b32_e32 v11, 0xffff0000, v5
	v_and_b32_e32 v13, 0xffff0000, v37
	v_pk_mul_f32 v[16:17], v[12:13], v[10:11]
	ds_read_b128 v[10:13], v181
	v_cvt_pk_bf16_f32 v5, v16, v17
	global_store_dwordx4 v[0:1], v[2:5], off
	ds_read_b128 v[0:3], v181 offset:1152
	s_waitcnt vmcnt(3)
	v_lshlrev_b32_e32 v16, 16, v38
	s_waitcnt lgkmcnt(1)
	v_lshlrev_b32_e32 v4, 16, v10
	v_and_b32_e32 v5, 0xffff0000, v10
	v_and_b32_e32 v17, 0xffff0000, v38
	v_pk_mul_f32 v[4:5], v[16:17], v[4:5]
	v_lshlrev_b32_e32 v16, 16, v39
	v_cvt_pk_bf16_f32 v10, v4, v5
	v_lshlrev_b32_e32 v4, 16, v11
	v_and_b32_e32 v5, 0xffff0000, v11
	v_and_b32_e32 v17, 0xffff0000, v39
	v_pk_mul_f32 v[4:5], v[16:17], v[4:5]
	v_lshlrev_b32_e32 v16, 16, v40
	v_cvt_pk_bf16_f32 v11, v4, v5
	v_lshlrev_b32_e32 v4, 16, v12
	v_and_b32_e32 v5, 0xffff0000, v12
	v_and_b32_e32 v17, 0xffff0000, v40
	v_pk_mul_f32 v[4:5], v[16:17], v[4:5]
	v_lshlrev_b32_e32 v16, 16, v41
	v_cvt_pk_bf16_f32 v12, v4, v5
	v_lshlrev_b32_e32 v4, 16, v13
	v_and_b32_e32 v5, 0xffff0000, v13
	v_and_b32_e32 v17, 0xffff0000, v41
	v_pk_mul_f32 v[4:5], v[16:17], v[4:5]
	s_waitcnt vmcnt(2)
	v_lshlrev_b32_e32 v16, 16, v45
	v_cvt_pk_bf16_f32 v13, v4, v5
	v_lshl_add_u64 v[4:5], s[26:27], 0, v[48:49]
	global_store_dwordx4 v[4:5], v[10:13], off
	s_waitcnt lgkmcnt(0)
	v_lshlrev_b32_e32 v4, 16, v0
	v_and_b32_e32 v5, 0xffff0000, v0
	v_lshlrev_b32_e32 v10, 16, v42
	v_and_b32_e32 v11, 0xffff0000, v42
	v_pk_mul_f32 v[4:5], v[10:11], v[4:5]
	v_lshlrev_b32_e32 v10, 16, v43
	v_cvt_pk_bf16_f32 v0, v4, v5
	v_lshlrev_b32_e32 v4, 16, v1
	v_and_b32_e32 v5, 0xffff0000, v1
	v_and_b32_e32 v11, 0xffff0000, v43
	v_pk_mul_f32 v[4:5], v[10:11], v[4:5]
	v_lshlrev_b32_e32 v10, 16, v44
	v_cvt_pk_bf16_f32 v1, v4, v5
	v_lshlrev_b32_e32 v4, 16, v2
	v_and_b32_e32 v5, 0xffff0000, v2
	v_and_b32_e32 v11, 0xffff0000, v44
	v_pk_mul_f32 v[4:5], v[10:11], v[4:5]
	ds_read_b128 v[10:13], v181 offset:2304
	v_cvt_pk_bf16_f32 v2, v4, v5
	v_lshlrev_b32_e32 v4, 16, v3
	v_and_b32_e32 v5, 0xffff0000, v3
	v_and_b32_e32 v17, 0xffff0000, v45
	v_pk_mul_f32 v[4:5], v[16:17], v[4:5]
	s_nop 0
	v_cvt_pk_bf16_f32 v3, v4, v5
	v_lshl_add_u64 v[4:5], s[26:27], 0, v[50:51]
	global_store_dwordx4 v[4:5], v[0:3], off
	s_waitcnt vmcnt(3)
	v_lshlrev_b32_e32 v4, 16, v7
	v_and_b32_e32 v5, 0xffff0000, v7
	s_waitcnt lgkmcnt(0)
	v_lshlrev_b32_e32 v0, 16, v10
	v_and_b32_e32 v1, 0xffff0000, v10
	v_lshlrev_b32_e32 v2, 16, v6
	v_and_b32_e32 v3, 0xffff0000, v6
	v_pk_mul_f32 v[0:1], v[2:3], v[0:1]
	v_lshlrev_b32_e32 v2, 16, v11
	v_and_b32_e32 v3, 0xffff0000, v11
	v_pk_mul_f32 v[2:3], v[4:5], v[2:3]
	v_cvt_pk_bf16_f32 v0, v0, v1
	v_cvt_pk_bf16_f32 v1, v2, v3
	v_lshlrev_b32_e32 v2, 16, v12
	v_and_b32_e32 v3, 0xffff0000, v12
	v_lshlrev_b32_e32 v4, 16, v8
	v_and_b32_e32 v5, 0xffff0000, v8
	v_pk_mul_f32 v[2:3], v[4:5], v[2:3]
	v_lshlrev_b32_e32 v4, 16, v13
	v_and_b32_e32 v5, 0xffff0000, v13
	v_lshlrev_b32_e32 v6, 16, v9
	v_and_b32_e32 v7, 0xffff0000, v9
	v_pk_mul_f32 v[4:5], v[6:7], v[4:5]
	v_cvt_pk_bf16_f32 v2, v2, v3
	v_cvt_pk_bf16_f32 v3, v4, v5
	v_lshl_add_u64 v[4:5], s[26:27], 0, v[14:15]
	global_store_dwordx4 v[4:5], v[0:3], off
	s_waitcnt lgkmcnt(0)
	s_barrier
.LBB0_642:
	s_add_i32 s6, s6, s74
	s_add_i32 s79, s79, s80
	s_add_i32 s81, s81, s82
	s_cmpk_lt_u32 s6, 0x700
	s_cbranch_scc0 .LBB0_687
